# sparse PART row stores write-through (sc1); v75 otherwise
# baseline (speedup 1.0000x reference)
.LBB0_844:
	s_or_b64 exec, exec, s[8:9]
	v_cvt_pk_bf16_f32 v48, v48, v49
	v_cvt_pk_bf16_f32 v49, v50, v51
	ds_write_b64 v204, v[48:49]
	v_cvt_pk_bf16_f32 v48, v52, v53
	v_cvt_pk_bf16_f32 v49, v54, v55
	v_cndmask_b32_e32 v64, -1, v64, vcc
	ds_write_b64 v204, v[48:49] offset:16
	v_cvt_pk_bf16_f32 v48, v56, v57
	v_cvt_pk_bf16_f32 v49, v58, v59
	ds_bpermute_b32 v176, v188, v64
	ds_write_b64 v204, v[48:49] offset:32
	v_cvt_pk_bf16_f32 v48, v60, v61
	v_cvt_pk_bf16_f32 v49, v62, v63
	ds_write_b64 v204, v[48:49] offset:48
	s_waitcnt lgkmcnt(0)
	ds_bpermute_b32 v64, v189, v64
	ds_read_b128 v[48:51], v205
	s_waitcnt lgkmcnt(4)
	v_lshlrev_b64 v[52:53], 8, v[176:177]
	v_cmp_lt_i32_e32 vcc, -1, v176
	v_lshl_add_u64 v[52:53], v[182:183], 0, v[52:53]
	v_add_u32_e32 v56, v179, v178
	s_and_saveexec_b64 s[8:9], vcc
	s_cbranch_execz .LBB0_846
	ds_read_b128 v[58:61], v56
	s_waitcnt lgkmcnt(0)
	global_store_dwordx4 v[52:53], v[58:61], off sc1
	s_add_u32 s98, s98, 1
.LBB0_846:
	s_or_b64 exec, exec, s[8:9]
	v_mov_b32_e32 v65, v177
	s_waitcnt lgkmcnt(1)
	v_lshlrev_b64 v[54:55], 8, v[64:65]
	v_cmp_lt_i32_e64 s[8:9], -1, v64
	v_lshl_add_u64 v[54:55], v[182:183], 0, v[54:55]
	s_and_saveexec_b64 s[30:31], s[8:9]
	s_cbranch_execz .LBB0_848
	s_waitcnt lgkmcnt(0)
	global_store_dwordx4 v[54:55], v[48:51], off sc1
	s_add_u32 s98, s98, 1
.LBB0_848:
	s_or_b64 exec, exec, s[30:31]
	s_waitcnt lgkmcnt(0)
	v_cvt_pk_bf16_f32 v32, v32, v33
	v_cvt_pk_bf16_f32 v33, v34, v35
	ds_write_b64 v204, v[32:33]
	v_cvt_pk_bf16_f32 v32, v36, v37
	v_cvt_pk_bf16_f32 v33, v38, v39
	ds_write_b64 v204, v[32:33] offset:16
	v_cvt_pk_bf16_f32 v32, v40, v41
	v_cvt_pk_bf16_f32 v33, v42, v43
	ds_write_b64 v204, v[32:33] offset:32
	v_cvt_pk_bf16_f32 v32, v44, v45
	v_cvt_pk_bf16_f32 v33, v46, v47
	ds_write_b64 v204, v[32:33] offset:48
	s_waitcnt lgkmcnt(0)
	ds_read_b128 v[32:35], v205
	s_and_saveexec_b64 s[30:31], vcc
	s_cbranch_execz .LBB0_850
	ds_read_b128 v[36:39], v56
	s_waitcnt lgkmcnt(0)
	global_store_dwordx4 v[52:53], v[36:39], off offset:64 sc1
	s_add_u32 s98, s98, 1
.LBB0_850:
	s_or_b64 exec, exec, s[30:31]
	s_and_saveexec_b64 s[30:31], s[8:9]
	s_cbranch_execz .LBB0_852
	s_waitcnt lgkmcnt(0)
	global_store_dwordx4 v[54:55], v[32:35], off offset:64 sc1
	s_add_u32 s98, s98, 1
.LBB0_852:
	s_or_b64 exec, exec, s[30:31]
	s_waitcnt lgkmcnt(0)
	v_cvt_pk_bf16_f32 v16, v16, v17
	v_cvt_pk_bf16_f32 v17, v18, v19
	ds_write_b64 v204, v[16:17]
	v_cvt_pk_bf16_f32 v16, v20, v21
	v_cvt_pk_bf16_f32 v17, v22, v23
	ds_write_b64 v204, v[16:17] offset:16
	v_cvt_pk_bf16_f32 v16, v24, v25
	v_cvt_pk_bf16_f32 v17, v26, v27
	ds_write_b64 v204, v[16:17] offset:32
	v_cvt_pk_bf16_f32 v16, v28, v29
	v_cvt_pk_bf16_f32 v17, v30, v31
	ds_write_b64 v204, v[16:17] offset:48
	s_waitcnt lgkmcnt(0)
	ds_read_b128 v[16:19], v205
	s_and_saveexec_b64 s[30:31], vcc
	s_cbranch_execz .LBB0_854
	ds_read_b128 v[20:23], v56
	s_waitcnt lgkmcnt(0)
	global_store_dwordx4 v[52:53], v[20:23], off offset:128 sc1
	s_add_u32 s98, s98, 1
.LBB0_854:
	s_or_b64 exec, exec, s[30:31]
	s_and_saveexec_b64 s[30:31], s[8:9]
	s_cbranch_execz .LBB0_856
	s_waitcnt lgkmcnt(0)
	global_store_dwordx4 v[54:55], v[16:19], off offset:128 sc1
	s_add_u32 s98, s98, 1
.LBB0_856:
	s_or_b64 exec, exec, s[30:31]
	s_waitcnt lgkmcnt(0)
	v_cvt_pk_bf16_f32 v0, v0, v1
	v_cvt_pk_bf16_f32 v1, v2, v3
	ds_write_b64 v204, v[0:1]
	v_cvt_pk_bf16_f32 v0, v4, v5
	v_cvt_pk_bf16_f32 v1, v6, v7
	ds_write_b64 v204, v[0:1] offset:16
	v_cvt_pk_bf16_f32 v0, v8, v9
	v_cvt_pk_bf16_f32 v1, v10, v11
	ds_write_b64 v204, v[0:1] offset:32
	v_cvt_pk_bf16_f32 v0, v12, v13
	v_cvt_pk_bf16_f32 v1, v14, v15
	ds_write_b64 v204, v[0:1] offset:48
	s_waitcnt lgkmcnt(0)
	ds_read_b128 v[0:3], v205
	s_and_saveexec_b64 s[30:31], vcc
	s_cbranch_execz .LBB0_858
	ds_read_b128 v[4:7], v56
	s_waitcnt lgkmcnt(0)
	global_store_dwordx4 v[52:53], v[4:7], off offset:192 sc1
	s_add_u32 s98, s98, 1
.LBB0_858:
	s_or_b64 exec, exec, s[30:31]
	s_and_saveexec_b64 s[30:31], s[8:9]
	s_cbranch_execz .LBB0_822
	s_waitcnt lgkmcnt(0)
	global_store_dwordx4 v[54:55], v[0:3], off offset:192 sc1
	s_add_u32 s98, s98, 1
	s_branch .LBB0_822
